# router top-2 position counters aggregated per block in LDS, one global atomic per block and expert
# speedup vs baseline: 1.0793x; 1.0793x over previous
; DI int otid() { int t = threadIdx.x & 255; asm volatile("" : "+v"(t)); return t; }
; DI void phase_ln(const Params& p, int l, int which, int bid, int nb) {
;     ...
;   const int tid_ = otid(); const int lane = tid_ & 63, wv = tid_ >> 6;
;   f4v nx[4];
;   {
;     const int row0 = bid * 4 + wv;
; #pragma unroll
;     for (int i = 0; i < 4; ++i) nx[i] = *(const f4v*)&out[(size_t)row0 * DM + 256 * i + lane * 4];
;   }
;   for (int row = bid * 4 + wv; row < SEQ; row += nb * 4) {
.LBB0_1405:
	s_or_b64 exec, exec, s[2:3]
	v_mov_b32_e32 v3, v181
	v_mov_b32_e32 v1, v182
	s_waitcnt lgkmcnt(0)
	s_barrier
	v_mov_b32_e32 v4, 0
	v_mov_b32_e32 v5, 0
	ds_write_b64 v0, v[4:5] offset:256
	ds_write_b64 v0, v[4:5] offset:264
	ds_write_b64 v0, v[4:5] offset:272
	ds_write_b64 v0, v[4:5] offset:280
	s_waitcnt lgkmcnt(0)
	s_barrier
	s_movk_i32 s2, 0x4000
	v_ashrrev_i32_e32 v2, 6, v1
	v_lshlrev_b32_e32 v4, 2, v3
	v_add_u32_e32 v50, v2, v4
	v_cmp_gt_i32_e32 vcc, s2, v50
	s_and_saveexec_b64 s[8:9], vcc
	s_cbranch_execz .LBB0_1418
	v_ashrrev_i32_e32 v51, 31, v50
	v_readlane_b32 s16, v252, 3
	v_and_b32_e32 v10, 63, v1
	v_lshlrev_b64 v[6:7], 12, v[50:51]
	v_readlane_b32 s18, v252, 5
	v_readlane_b32 s19, v252, 6
	v_lshlrev_b32_e32 v8, 4, v10
	v_mov_b32_e32 v9, v0
	v_lshl_add_u64 v[6:7], s[18:19], 0, v[6:7]
	v_lshl_add_u64 v[6:7], v[6:7], 0, v[8:9]
	global_load_dwordx4 v[18:21], v[6:7], off offset:3072
	global_load_dwordx4 v[22:25], v[6:7], off offset:2048
	global_load_dwordx4 v[26:29], v[6:7], off offset:1024
	global_load_dwordx4 v[30:33], v[6:7], off
	v_and_b32_e32 v1, 64, v196
	v_add_u32_e32 v5, 64, v1
	v_xor_b32_e32 v1, 32, v196
	v_cmp_lt_i32_e32 vcc, v1, v5
	v_xor_b32_e32 v6, 16, v196
	v_readlane_b32 s4, v255, 30
	v_cndmask_b32_e32 v1, v196, v1, vcc
	v_cmp_lt_i32_e32 vcc, v6, v5
	v_readlane_b32 s6, v255, 32
	v_readlane_b32 s5, v255, 31
	v_cndmask_b32_e32 v6, v196, v6, vcc
	v_lshlrev_b32_e32 v51, 2, v6
	v_xor_b32_e32 v6, 8, v196
	v_cmp_lt_i32_e32 vcc, v6, v5
	s_lshl_b32 s2, s6, 10
	s_mov_b32 s3, s5
	v_cndmask_b32_e32 v6, v196, v6, vcc
	v_lshlrev_b32_e32 v80, 2, v6
	v_xor_b32_e32 v6, 4, v196
	v_readlane_b32 s40, v252, 27
	v_cmp_lt_i32_e32 vcc, v6, v5
	s_lshl_b64 s[4:5], s[2:3], 2
	v_readlane_b32 s54, v252, 41
	v_cndmask_b32_e32 v6, v196, v6, vcc
	v_readlane_b32 s55, v252, 42
	s_add_u32 s2, s54, s4
	v_lshlrev_b32_e32 v81, 2, v6
	v_xor_b32_e32 v6, 2, v196
	v_readlane_b32 s52, v252, 39
	s_addc_u32 s3, s55, s5
	v_cmp_lt_i32_e32 vcc, v6, v5
	v_readlane_b32 s41, v252, 28
	v_readlane_b32 s42, v252, 29
	v_readlane_b32 s43, v252, 30
	v_readlane_b32 s44, v252, 31
	v_readlane_b32 s45, v252, 32
	v_readlane_b32 s46, v252, 33
	v_readlane_b32 s47, v252, 34
	v_readlane_b32 s48, v252, 35
	v_readlane_b32 s49, v252, 36
	v_readlane_b32 s50, v252, 37
	v_readlane_b32 s51, v252, 38
	v_readlane_b32 s53, v252, 40
	s_add_u32 s4, s52, s4
	v_cndmask_b32_e32 v6, v196, v6, vcc
	s_addc_u32 s5, s53, s5
	v_lshlrev_b32_e32 v82, 2, v6
	v_xor_b32_e32 v6, 1, v196
	s_lshl_b32 s6, s6, 14
	v_readlane_b32 s40, v252, 43
	v_cmp_lt_i32_e32 vcc, v6, v5
	s_and_b32 s6, s6, 0x8000
	v_readlane_b32 s50, v252, 53
	v_cndmask_b32_e32 v5, v196, v6, vcc
	v_lshl_add_u64 v[56:57], s[2:3], 0, v[8:9]
	v_lshlrev_b32_e32 v6, 7, v10
	v_readlane_b32 s51, v252, 54
	s_add_u32 s2, s50, s6
	v_lshl_add_u64 v[52:53], s[18:19], 0, v[8:9]
	v_lshl_add_u64 v[54:55], s[4:5], 0, v[8:9]
	s_addc_u32 s3, s51, 0
	v_mov_b32_e32 v7, v0
	v_or_b32_e32 v8, 0x2000, v6
	v_lshlrev_b32_e32 v83, 2, v5
	v_lshl_add_u64 v[58:59], s[2:3], 0, v[6:7]
	v_lshl_add_u64 v[60:61], s[2:3], 0, v[8:9]
	v_or_b32_e32 v8, 0x4000, v6
	v_or_b32_e32 v6, 0x6000, v6
	v_lshlrev_b32_e32 v5, 1, v2
	v_lshl_add_u64 v[64:65], s[2:3], 0, v[8:9]
	v_lshl_add_u64 v[68:69], s[2:3], 0, v[6:7]
	s_mov_b64 s[2:3], 0x6040
	v_lshl_add_u32 v3, v3, 3, v5
	v_lshl_add_u64 v[70:71], v[58:59], 0, s[2:3]
	v_or_b32_e32 v72, 1, v3
	v_readlane_b32 s2, v255, 18
	v_ashrrev_i32_e32 v3, 31, v2
	v_ashrrev_i32_e32 v5, 31, v4
	v_readlane_b32 s3, v255, 19
	v_add3_u32 v6, s2, v2, v4
	v_lshl_add_u64 v[2:3], v[2:3], 0, v[4:5]
	v_lshlrev_b64 v[76:77], 12, v[2:3]
	v_lshlrev_b64 v[2:3], 11, v[2:3]
	v_readlane_b32 s2, v255, 16
	s_mov_b64 s[4:5], 0x2040
	v_ashrrev_i32_e32 v7, 31, v6
	v_lshl_or_b32 v2, v10, 3, v2
	v_readlane_b32 s3, v255, 17
	v_cmp_eq_u32_e64 s[38:39], 0, v10
	v_lshl_add_u64 v[62:63], v[58:59], 0, s[4:5]
	s_mov_b64 s[4:5], 0x4040
	v_lshlrev_b64 v[74:75], 12, v[6:7]
	v_lshl_add_u64 v[78:79], s[2:3], 0, v[2:3]
	s_waitcnt vmcnt(3)
	v_mov_b64_e32 v[2:3], v[18:19]
	s_waitcnt vmcnt(2)
	v_mov_b64_e32 v[6:7], v[22:23]
	s_waitcnt vmcnt(1)
	v_mov_b64_e32 v[10:11], v[26:27]
	s_waitcnt vmcnt(0)
	v_mov_b64_e32 v[14:15], v[30:31]
	v_lshlrev_b32_e32 v1, 2, v1
	v_lshl_add_u64 v[66:67], v[58:59], 0, s[4:5]
	s_mov_b64 s[34:35], 0
	v_mov_b64_e32 v[4:5], v[20:21]
	v_mov_b64_e32 v[8:9], v[24:25]
	v_mov_b64_e32 v[12:13], v[28:29]
	v_mov_b64_e32 v[16:17], v[32:33]
	v_readlane_b32 s7, v255, 33
	v_readlane_b32 s17, v252, 4
	v_readlane_b32 s20, v252, 7
	v_readlane_b32 s21, v252, 8
	v_readlane_b32 s22, v252, 9
	v_readlane_b32 s23, v252, 10
	v_readlane_b32 s41, v252, 44
	v_readlane_b32 s42, v252, 45
	v_readlane_b32 s43, v252, 46
	v_readlane_b32 s44, v252, 47
	v_readlane_b32 s45, v252, 48
	v_readlane_b32 s46, v252, 49
	v_readlane_b32 s47, v252, 50
	v_readlane_b32 s48, v252, 51
	v_readlane_b32 s49, v252, 52
	v_readlane_b32 s52, v252, 55
	v_readlane_b32 s53, v252, 56
	v_readlane_b32 s54, v252, 57
	v_readlane_b32 s55, v252, 58
	s_branch .LBB0_1411

; DI void phase_ln(const Params& p, int l, int which, int bid, int nb) {
;     ...
;         const float g1 = 1.f / (1.f + __expf(b2 - b1)), g2 = 1.f - g1;
;         int* cnt = (int*)(ws + MOE_CNT);
;         int* te = (int*)(ws + MOE_TE); int* tp = (int*)(ws + MOE_TP); float* tg = (float*)(ws + MOE_TG);
;         te[row * 2] = i1; te[row * 2 + 1] = i2;
;         tp[row * 2] = atomicAdd(&cnt[i1], 1); tp[row * 2 + 1] = atomicAdd(&cnt[i2], 1);
;         tg[row * 2] = g1; tg[row * 2 + 1] = g2;
.LBB0_1408:
	s_or_b64 exec, exec, s[4:5]
	v_sub_f32_e32 v19, v21, v32
	v_mul_f32_e32 v19, 0x3fb8aa3b, v19
	v_exp_f32_e32 v19, v19
	v_ashrrev_i32_e32 v73, 31, v72
	v_readlane_b32 s4, v254, 62
	v_readlane_b32 s5, v254, 63
	v_add_f32_e32 v19, 1.0, v19
	v_div_scale_f32 v21, s[2:3], v19, v19, 1.0
	v_rcp_f32_e32 v22, v21
	v_readlane_b32 s2, v254, 60
	v_readlane_b32 s3, v254, 61
	v_fma_f32 v23, -v21, v22, 1.0
	v_fmac_f32_e32 v22, v23, v22
	v_div_scale_f32 v23, vcc, 1.0, v19, 1.0
	v_mul_f32_e32 v24, v23, v22
	v_fma_f32 v25, -v21, v24, v23
	v_fmac_f32_e32 v24, v25, v22
	v_fma_f32 v21, -v21, v24, v23
	v_div_fmas_f32 v21, v21, v22, v24
	v_add_u32_e32 v22, -1, v72
	v_ashrrev_i32_e32 v23, 31, v22
	v_lshlrev_b64 v[22:23], 2, v[22:23]
	v_lshl_add_u64 v[24:25], s[2:3], 0, v[22:23]
	global_store_dword v[24:25], v18, off
	v_lshlrev_b64 v[24:25], 2, v[72:73]
	v_lshl_add_u64 v[26:27], s[2:3], 0, v[24:25]
	v_div_fixup_f32 v28, v21, v19, 1.0
	global_store_dword v[26:27], v20, off
	v_sub_f32_e32 v29, 1.0, v28
	v_lshlrev_b32_e32 v19, 2, v18
	v_lshlrev_b32_e32 v21, 2, v20
	ds_add_rtn_u32 v26, v19, v186 offset:256
	ds_add_rtn_u32 v27, v21, v186 offset:256
	v_lshrrev_b32_e32 v19, 12, v72
	v_and_b32_e32 v21, 15, v72
	v_lshl_or_b32 v19, v19, 4, v21
	v_lshlrev_b32_e32 v19, 3, v19
	v_readlane_b32 s2, v255, 0
	v_readlane_b32 s3, v255, 1
	s_waitcnt lgkmcnt(0)
	ds_write2_b32 v19, v18, v26 offset0:126 offset1:127
	ds_write2_b32 v19, v20, v27 offset0:128 offset1:129
	s_waitcnt lgkmcnt(0)
	v_lshl_add_u64 v[18:19], s[2:3], 0, v[22:23]
	global_store_dword v[18:19], v28, off
	v_lshl_add_u64 v[18:19], s[2:3], 0, v[24:25]
	global_store_dword v[18:19], v29, off

; DI void phase_ln(const Params& p, int l, int which, int bid, int nb) {
;     ...
;         int* cnt = (int*)(ws + MOE_CNT);
;         int* te = (int*)(ws + MOE_TE); int* tp = (int*)(ws + MOE_TP); float* tg = (float*)(ws + MOE_TG);
;         te[row * 2] = i1; te[row * 2 + 1] = i2;
;         tp[row * 2] = atomicAdd(&cnt[i1], 1); tp[row * 2 + 1] = atomicAdd(&cnt[i2], 1);
;         tg[row * 2] = g1; tg[row * 2 + 1] = g2;
; DI void xcd_barrier(const XcdBarrier& b) {
;   asm volatile("s_waitcnt vmcnt(0)" ::: "memory");
;   __syncthreads();
;   if (threadIdx.x == 0) {
;     unsigned* bar = b.bar;
;     __builtin_amdgcn_s_waitcnt(0);
;     unsigned nloc = b.st[0], nx = b.st[1];
;     if (nloc == 0u) { xcd_barrier_complete(bar, b.x, nloc, nx); b.st[0] = nloc; b.st[1] = nx; }
.LBB0_1418:
	s_or_b64 exec, exec, s[8:9]
	v_readlane_b32 s2, v255, 34
	v_readlane_b32 s3, v255, 35
	s_nop 3
	s_cmp_eq_u64 s[2:3], 0
	s_cbranch_scc1 .Lrt_done
	s_waitcnt lgkmcnt(0)
	s_barrier
	v_readlane_b32 s2, v254, 29
	v_readlane_b32 s3, v254, 30
	v_readlane_b32 s4, v252, 0
	v_lshrrev_b32_e32 v6, 4, v180
	v_and_b32_e32 v7, 15, v180
	s_lshl_b32 s4, s4, 4
	v_lshl_or_b32 v6, v6, 12, v7
	v_add_u32_e32 v6, s4, v6
	v_lshlrev_b32_e32 v6, 2, v6
	v_cmp_gt_u32_e32 vcc, 8, v180
	s_and_saveexec_b64 s[4:5], vcc
	s_cbranch_execz .Lrt_a
	v_lshlrev_b32_e32 v2, 2, v180
	ds_read_b32 v3, v2 offset:256
	s_waitcnt lgkmcnt(0)
	global_atomic_add v3, v2, v3, s[2:3] sc0
	s_waitcnt vmcnt(0)
	ds_write_b32 v2, v3 offset:288
.Lrt_a:
	s_or_b64 exec, exec, s[4:5]
	s_waitcnt lgkmcnt(0)
	s_barrier
	v_readlane_b32 s2, v254, 62
	v_readlane_b32 s3, v254, 63
	v_cmp_gt_u32_e32 vcc, 0x80, v180
	s_and_saveexec_b64 s[4:5], vcc
	s_cbranch_execz .Lrt_b
	v_lshlrev_b32_e32 v2, 3, v180
	ds_read2_b32 v[4:5], v2 offset0:128 offset1:129
	s_waitcnt lgkmcnt(0)
	v_lshlrev_b32_e32 v4, 2, v4
	ds_read_b32 v4, v4 offset:288
	s_waitcnt lgkmcnt(0)
	v_add_u32_e32 v4, v4, v5
	global_store_dword v6, v4, s[2:3]
.Lrt_b:
	s_or_b64 exec, exec, s[4:5]
.Lrt_done:
	s_waitcnt vmcnt(0)
	s_barrier
	s_mov_b64 s[2:3], exec
	v_readlane_b32 s4, v252, 1
	v_readlane_b32 s5, v252, 2
	s_and_b64 s[4:5], s[2:3], s[4:5]
	s_mov_b64 exec, s[4:5]
	s_cbranch_execz .LBB0_1466
	s_waitcnt vmcnt(0) expcnt(0) lgkmcnt(0)
	ds_read_b32 v3, v0
	ds_read_b32 v2, v0 offset:4
	s_waitcnt lgkmcnt(1)
	v_cmp_ne_u32_e32 vcc, 0, v3
	s_cbranch_vccnz .LBB0_1434
	s_mov_b32 s16, 1
	s_branch .LBB0_1422
